# scan compute waves: U fragments and exp(g_last) prefetched two chunks ahead in alternating register sets
# speedup vs baseline: 1.0089x; 1.0089x over previous
; #define LDSBAR() do { asm volatile("s_waitcnt lgkmcnt(0)" ::: "memory"); __builtin_amdgcn_s_barrier(); asm volatile("" ::: "memory"); } while (0)
; DI void gdn_scan(const Args& a, int l, int bh, LAS unsigned char* lds, const int tidx, const bool nostore) {
;     ...
;     if (wave < 4) {
;         __builtin_amdgcn_s_setprio(2);
;         f32x16 S[4];
; #pragma unroll
;         for (int t = 0; t < 4; ++t)
; #pragma unroll
;             for (int r = 0; r < 16; ++r) S[t][r] = 0.f;
;         u32x4 un[2][2]; float egn;
; #pragma unroll
;         for (int mt = 0; mt < 2; ++mt) { const u32x4* up = (const u32x4*)urec + ((size_t)((wave * 2 + mt) * 64 + lane)) * 2; un[mt][0] = up[0]; un[mt][1] = up[1]; }
;         egn = egl[0];
;         LDSBAR();
;         for (int n = 0; n < 64; ++n) {
.LBB0_378:
	s_and_b64 vcc, exec, s[0:1]
	s_cbranch_vccz .LBB0_382
	s_lshl_b64 s[4:5], s[96:97], 20
	s_add_u32 s0, s58, s4
	s_addc_u32 s1, s59, s5
	s_add_u32 s0, s0, 0x1a900000
	s_addc_u32 s1, s1, 0
	s_lshl_b32 s6, s96, 6
	s_ashr_i32 s7, s6, 31
	s_lshl_b64 s[6:7], s[6:7], 2
	v_mov_b64_e32 v[206:207], 0x1ff
	s_add_u32 s8, s58, s6
	v_and_b32_e32 v6, 63, v220
	s_addc_u32 s9, s59, s7
	s_setprio 2
	v_lshl_or_b32 v0, s11, 7, v6
	v_ashrrev_i32_e32 v1, 31, v0
	v_lshlrev_b64 v[2:3], 5, v[0:1]
	v_or_b32_e32 v0, 64, v0
	v_ashrrev_i32_e32 v1, 31, v0
	v_lshl_add_u64 v[4:5], s[0:1], 0, v[2:3]
	v_lshlrev_b64 v[0:1], 5, v[0:1]
	global_load_dwordx4 v[212:215], v[4:5], off offset:16
	global_load_dwordx4 v[208:211], v[4:5], off
	v_lshl_add_u64 v[4:5], s[0:1], 0, v[0:1]
	global_load_dwordx4 v[240:243], v[4:5], off offset:16
	global_load_dwordx4 v[216:219], v[4:5], off
	v_mov_b32_e32 v4, 0x64c0000
	global_load_dword v221, v4, s[8:9]
	s_add_u32 s12, s0, 0x4000
	s_addc_u32 s13, s1, 0
	v_lshl_add_u64 v[8:9], s[12:13], 0, v[2:3]
	global_load_dwordx4 v[128:131], v[8:9], off offset:16
	global_load_dwordx4 v[132:135], v[8:9], off
	v_lshl_add_u64 v[8:9], s[12:13], 0, v[0:1]
	global_load_dwordx4 v[136:139], v[8:9], off offset:16
	global_load_dwordx4 v[140:143], v[8:9], off
	global_load_dword v151, v4, s[8:9] offset:4
	v_lshrrev_b32_e32 v4, 3, v220
	s_andn2_b32 s10, s10, 63
	v_and_b32_e32 v4, 4, v4
	s_add_i32 s0, s10, 0
	v_and_b32_e32 v5, 31, v220
	v_mul_u32_u24_e32 v4, 0x110, v4
	s_add_i32 s0, s0, 0x1c000
	v_lshlrev_b32_e32 v5, 1, v5
	v_add3_u32 v149, s0, v4, v5
	v_readlane_b32 s0, v253, 61
	s_add_u32 s0, s0, s6
	v_readlane_b32 s1, v253, 62
	s_addc_u32 s1, s1, s7
	s_add_u32 s4, s42, s4
	s_waitcnt lgkmcnt(0)
	s_barrier
	s_addc_u32 s5, s43, s5
	v_lshl_add_u64 v[146:147], s[4:5], 0, v[0:1]
	v_mov_b32_e32 v0, 0
	v_lshl_add_u32 v150, v6, 4, 0
	v_lshl_add_u64 v[144:145], s[4:5], 0, v[2:3]
	s_mov_b32 s4, 0
	v_mov_b32_e32 v1, v0
	v_mov_b32_e32 v2, v0
	v_mov_b32_e32 v3, v0
	v_mov_b32_e32 v4, v0
	v_mov_b32_e32 v5, v0
	v_mov_b32_e32 v6, v0
	v_mov_b32_e32 v7, v0
	v_mov_b32_e32 v8, v0
	v_mov_b32_e32 v9, v0
	v_mov_b32_e32 v10, v0
	v_mov_b32_e32 v11, v0
	v_mov_b32_e32 v12, v0
	v_mov_b32_e32 v13, v0
	v_mov_b32_e32 v14, v0
	v_mov_b32_e32 v15, v0
	v_mov_b32_e32 v16, v0
	v_mov_b32_e32 v17, v0
	v_mov_b32_e32 v18, v0
	v_mov_b32_e32 v19, v0
	v_mov_b32_e32 v20, v0
	v_mov_b32_e32 v21, v0
	v_mov_b32_e32 v22, v0
	v_mov_b32_e32 v23, v0
	v_mov_b32_e32 v24, v0
	v_mov_b32_e32 v25, v0
	v_mov_b32_e32 v26, v0
	v_mov_b32_e32 v27, v0
	v_mov_b32_e32 v28, v0
	v_mov_b32_e32 v29, v0
	v_mov_b32_e32 v30, v0
	v_mov_b32_e32 v31, v0
	v_mov_b32_e32 v32, v0
	v_mov_b32_e32 v33, v0
	v_mov_b32_e32 v34, v0
	v_mov_b32_e32 v35, v0
	v_mov_b32_e32 v36, v0
	v_mov_b32_e32 v37, v0
	v_mov_b32_e32 v38, v0
	v_mov_b32_e32 v39, v0
	v_mov_b32_e32 v40, v0
	v_mov_b32_e32 v41, v0
	v_mov_b32_e32 v42, v0
	v_mov_b32_e32 v43, v0
	v_mov_b32_e32 v44, v0
	v_mov_b32_e32 v45, v0
	v_mov_b32_e32 v46, v0
	v_mov_b32_e32 v47, v0
	v_mov_b32_e32 v48, v0
	v_mov_b32_e32 v49, v0
	v_mov_b32_e32 v50, v0
	v_mov_b32_e32 v51, v0
	v_mov_b32_e32 v52, v0
	v_mov_b32_e32 v53, v0
	v_mov_b32_e32 v54, v0
	v_mov_b32_e32 v55, v0
	s_waitcnt vmcnt(0)
	v_mov_b32_e32 v56, v0
	v_mov_b32_e32 v57, v0
	v_mov_b32_e32 v58, v0
	v_mov_b32_e32 v59, v0
	s_waitcnt vmcnt(17)
	v_mov_b32_e32 v60, v0
	v_mov_b32_e32 v61, v0
	v_mov_b32_e32 v62, v0
	v_mov_b32_e32 v63, v0
	s_mov_b32 s8, 0x1a908000
	s_mov_b64 s[10:11], 0x4000
	s_mov_b64 s[12:13], 0x1a908000
.LBB0_380:
	s_waitcnt vmcnt(5)
	s_bitcmp1_b32 s4, 0
	s_cbranch_scc1 .Lscan_top_odd
	v_mov_b32_e32 v148, v221
	v_lshl_add_u64 v[64:65], v[144:145], 0, s[94:95]
	v_lshl_add_u64 v[66:67], v[64:65], 0, s[12:13]
	v_add_co_u32_e32 v64, vcc, s8, v64
	s_nop 0
	v_lshlrev_b32_e32 v112, 16, v208
	v_addc_co_u32_e32 v65, vcc, 0, v65, vcc
	v_and_b32_e32 v113, 0xffff0000, v208
	v_lshlrev_b32_e32 v114, 16, v209
	v_and_b32_e32 v115, 0xffff0000, v209
	v_lshlrev_b32_e32 v116, 16, v210
	v_and_b32_e32 v117, 0xffff0000, v210
	v_lshlrev_b32_e32 v118, 16, v211
	v_and_b32_e32 v119, 0xffff0000, v211
	v_lshlrev_b32_e32 v120, 16, v212
	v_and_b32_e32 v121, 0xffff0000, v212
	v_lshlrev_b32_e32 v122, 16, v213
	v_and_b32_e32 v123, 0xffff0000, v213
	v_lshlrev_b32_e32 v124, 16, v214
	v_and_b32_e32 v125, 0xffff0000, v214
	v_lshlrev_b32_e32 v126, 16, v215
	v_and_b32_e32 v127, 0xffff0000, v215
	global_load_dwordx4 v[208:211], v[64:65], off
	global_load_dwordx4 v[212:215], v[66:67], off offset:16
	v_lshl_add_u64 v[64:65], v[146:147], 0, s[94:95]
	v_lshl_add_u64 v[66:67], v[64:65], 0, s[12:13]
	v_add_co_u32_e32 v64, vcc, s8, v64
	s_add_u32 s6, s0, s94
	s_nop 0
	v_addc_co_u32_e32 v65, vcc, 0, v65, vcc
	s_nop 0
	v_lshlrev_b32_e32 v96, 16, v216
	v_and_b32_e32 v97, 0xffff0000, v216
	v_lshlrev_b32_e32 v98, 16, v217
	v_and_b32_e32 v99, 0xffff0000, v217
	v_lshlrev_b32_e32 v100, 16, v218
	v_and_b32_e32 v101, 0xffff0000, v218
	v_lshlrev_b32_e32 v102, 16, v219
	v_and_b32_e32 v103, 0xffff0000, v219
	v_lshlrev_b32_e32 v104, 16, v240
	v_and_b32_e32 v105, 0xffff0000, v240
	v_lshlrev_b32_e32 v106, 16, v241
	v_and_b32_e32 v107, 0xffff0000, v241
	v_lshlrev_b32_e32 v108, 16, v242
	v_and_b32_e32 v109, 0xffff0000, v242
	v_lshlrev_b32_e32 v110, 16, v243
	v_and_b32_e32 v111, 0xffff0000, v243
	global_load_dwordx4 v[216:219], v[64:65], off
	global_load_dwordx4 v[240:243], v[66:67], off offset:16
	s_addc_u32 s7, s1, s95
	global_load_dword v221, v205, s[6:7] offset:4
	s_branch .Lscan_top_done
; #define LAS __attribute__((address_space(3)))
; #define SBAR() __builtin_amdgcn_sched_barrier(0)
; #define LOAD_WQ(f, g) do { _Pragma("unroll") for (int e = 0; e < 2; ++e) { f[4 * e] = LDF((2 * (g) + e) * 1024); f[4 * e + 1] = LDF((8 + 2 * (g) + e) * 1024); \
;                 f[4 * e + 2] = LDF(16384 + (2 * (g) + e) * 1024); f[4 * e + 3] = LDF(16384 + (8 + 2 * (g) + e) * 1024); } } while (0)
; #define COMP_WQ(f, g) do { _Pragma("unroll") for (int e = 0; e < 2; ++e) { const bf16x8 sb = PACK8(S[(2 * (g) + e) >> 1], ((2 * (g) + e) & 1) * 8); \
;                 vn[0] = MFMA32(f[4 * e], sb, vn[0]); vn[1] = MFMA32(f[4 * e + 1], sb, vn[1]); o[0] = MFMA32(f[4 * e + 2], sb, o[0]); o[1] = MFMA32(f[4 * e + 3], sb, o[1]); } } while (0)
; DI void gdn_scan(const Args& a, int l, int bh, LAS unsigned char* lds, const int tidx, const bool nostore) {
;     ...
;         for (int n = 0; n < 64; ++n) {
;             f32x16 vn[2], o[2]; const float eg = egn;
; #pragma unroll
;             for (int mt = 0; mt < 2; ++mt) {
; #pragma unroll
;                 for (int g8 = 0; g8 < 2; ++g8) { const u32x4 u = un[mt][g8];
;                     vn[mt][8 * g8] = bflo(u.x); vn[mt][8 * g8 + 1] = bfhi(u.x); vn[mt][8 * g8 + 2] = bflo(u.y); vn[mt][8 * g8 + 3] = bfhi(u.y);
;                     vn[mt][8 * g8 + 4] = bflo(u.z); vn[mt][8 * g8 + 5] = bfhi(u.z); vn[mt][8 * g8 + 6] = bflo(u.w); vn[mt][8 * g8 + 7] = bfhi(u.w); }
; #pragma unroll
;                 for (int r = 0; r < 16; ++r) o[mt][r] = 0.f; }
;             if (n < 63) {
; #pragma unroll
;                 for (int mt = 0; mt < 2; ++mt) { const u32x4* up = (const u32x4*)(urec + (size_t)(n + 1) * 16384) + ((size_t)((wave * 2 + mt) * 64 + lane)) * 2; un[mt][0] = up[0]; un[mt][1] = up[1]; }
;                 egn = egl[n + 1];
;             }
;             const LAS unsigned char* buf = lds + (n & 1) * REC_BYTES + lane * 16;
;             bf16x8 fa[8], fb[8];
;     ...
;             LOAD_WQ(fa, 0); SBAR(); LOAD_WQ(fb, 1); SBAR();
;             COMP_WQ(fa, 0); SBAR(); LOAD_WQ(fa, 2); SBAR();
;             COMP_WQ(fb, 1); SBAR(); LOAD_WQ(fb, 3); SBAR();
.Lscan_top_odd:
	v_mov_b32_e32 v148, v151
	v_lshl_add_u64 v[64:65], v[144:145], 0, s[94:95]
	v_lshl_add_u64 v[66:67], v[64:65], 0, s[12:13]
	v_add_co_u32_e32 v64, vcc, s8, v64
	s_nop 0
	v_lshlrev_b32_e32 v112, 16, v132
	v_addc_co_u32_e32 v65, vcc, 0, v65, vcc
	v_and_b32_e32 v113, 0xffff0000, v132
	v_lshlrev_b32_e32 v114, 16, v133
	v_and_b32_e32 v115, 0xffff0000, v133
	v_lshlrev_b32_e32 v116, 16, v134
	v_and_b32_e32 v117, 0xffff0000, v134
	v_lshlrev_b32_e32 v118, 16, v135
	v_and_b32_e32 v119, 0xffff0000, v135
	v_lshlrev_b32_e32 v120, 16, v128
	v_and_b32_e32 v121, 0xffff0000, v128
	v_lshlrev_b32_e32 v122, 16, v129
	v_and_b32_e32 v123, 0xffff0000, v129
	v_lshlrev_b32_e32 v124, 16, v130
	v_and_b32_e32 v125, 0xffff0000, v130
	v_lshlrev_b32_e32 v126, 16, v131
	v_and_b32_e32 v127, 0xffff0000, v131
	global_load_dwordx4 v[132:135], v[64:65], off
	global_load_dwordx4 v[128:131], v[66:67], off offset:16
	v_lshl_add_u64 v[64:65], v[146:147], 0, s[94:95]
	v_lshl_add_u64 v[66:67], v[64:65], 0, s[12:13]
	v_add_co_u32_e32 v64, vcc, s8, v64
	s_add_u32 s6, s0, s94
	s_nop 0
	v_addc_co_u32_e32 v65, vcc, 0, v65, vcc
	s_nop 0
	v_lshlrev_b32_e32 v96, 16, v140
	v_and_b32_e32 v97, 0xffff0000, v140
	v_lshlrev_b32_e32 v98, 16, v141
	v_and_b32_e32 v99, 0xffff0000, v141
	v_lshlrev_b32_e32 v100, 16, v142
	v_and_b32_e32 v101, 0xffff0000, v142
	v_lshlrev_b32_e32 v102, 16, v143
	v_and_b32_e32 v103, 0xffff0000, v143
	v_lshlrev_b32_e32 v104, 16, v136
	v_and_b32_e32 v105, 0xffff0000, v136
	v_lshlrev_b32_e32 v106, 16, v137
	v_and_b32_e32 v107, 0xffff0000, v137
	v_lshlrev_b32_e32 v108, 16, v138
	v_and_b32_e32 v109, 0xffff0000, v138
	v_lshlrev_b32_e32 v110, 16, v139
	v_and_b32_e32 v111, 0xffff0000, v139
	global_load_dwordx4 v[140:143], v[64:65], off
	global_load_dwordx4 v[136:139], v[66:67], off offset:16
	s_addc_u32 s7, s1, s95
	global_load_dword v151, v205, s[6:7] offset:4
.Lscan_top_done:
	s_and_b32 s5, s4, 1
	s_mul_i32 s6, s5, 0xe000
	v_add_u32_e32 v204, s6, v150
	ds_read_b128 v[152:155], v204
	ds_read_b128 v[156:159], v204 offset:8192
	ds_read_b128 v[64:67], v204 offset:16384
	ds_read_b128 v[68:71], v204 offset:24576
	ds_read_b128 v[160:163], v204 offset:1024
	ds_read_b128 v[164:167], v204 offset:9216
	ds_read_b128 v[168:171], v204 offset:17408
	ds_read_b128 v[172:175], v204 offset:25600
	ds_read_b128 v[176:179], v204 offset:2048
	ds_read_b128 v[180:183], v204 offset:3072
	ds_read_b128 v[184:187], v204 offset:10240
	ds_read_b128 v[188:191], v204 offset:11264
	ds_read_b128 v[192:195], v204 offset:18432
	ds_read_b128 v[196:199], v204 offset:19456
	ds_read_b128 v[200:203], v204 offset:26624
	ds_read_b128 v[222:225], v204 offset:27648
	v_cvt_pk_bf16_f32 v226, v48, v49
	v_cvt_pk_bf16_f32 v227, v50, v51
	v_cvt_pk_bf16_f32 v228, v52, v53
	v_cvt_pk_bf16_f32 v229, v54, v55
	v_cvt_pk_bf16_f32 v230, v56, v57
	v_cvt_pk_bf16_f32 v231, v58, v59
	s_waitcnt lgkmcnt(13)
	v_mfma_f32_32x32x16_bf16 v[80:95], v[64:67], v[226:229], 0
	v_cvt_pk_bf16_f32 v232, v60, v61
	v_cvt_pk_bf16_f32 v233, v62, v63
	s_waitcnt lgkmcnt(12)
	v_mfma_f32_32x32x16_bf16 v[64:79], v[68:71], v[226:229], 0
	s_waitcnt lgkmcnt(9)
	v_mfma_f32_32x32x16_bf16 v[80:95], v[168:171], v[230:233], v[80:95]
	s_waitcnt lgkmcnt(8)
	v_mfma_f32_32x32x16_bf16 v[64:79], v[172:175], v[230:233], v[64:79]
	v_mfma_f32_32x32x16_bf16 v[112:127], v[152:155], v[226:229], v[112:127]
	v_mfma_f32_32x32x16_bf16 v[96:111], v[156:159], v[226:229], v[96:111]
	v_mfma_f32_32x32x16_bf16 v[112:127], v[160:163], v[230:233], v[112:127]
	ds_read_b128 v[152:155], v204 offset:4096
	ds_read_b128 v[156:159], v204 offset:5120
	ds_read_b128 v[160:163], v204 offset:12288
	ds_read_b128 v[168:171], v204 offset:13312
	ds_read_b128 v[172:175], v204 offset:20480
	ds_read_b128 v[226:229], v204 offset:21504
	ds_read_b128 v[234:237], v204 offset:28672
	ds_read_b128 v[248:251], v204 offset:29696
	v_mfma_f32_32x32x16_bf16 v[96:111], v[164:167], v[230:233], v[96:111]
	v_cvt_pk_bf16_f32 v164, v32, v33
	v_cvt_pk_bf16_f32 v165, v34, v35
	v_cvt_pk_bf16_f32 v166, v36, v37
	v_cvt_pk_bf16_f32 v167, v38, v39
	s_waitcnt lgkmcnt(11)
	s_nop 0
	v_mfma_f32_32x32x16_bf16 v[80:95], v[192:195], v[164:167], v[80:95]
	v_cvt_pk_bf16_f32 v192, v40, v41
	v_cvt_pk_bf16_f32 v193, v42, v43
	v_cvt_pk_bf16_f32 v194, v44, v45
	v_cvt_pk_bf16_f32 v195, v46, v47
	s_waitcnt lgkmcnt(9)
	v_mfma_f32_32x32x16_bf16 v[64:79], v[200:203], v[164:167], v[64:79]
	v_mfma_f32_32x32x16_bf16 v[80:95], v[196:199], v[192:195], v[80:95]
	s_waitcnt lgkmcnt(8)
	v_mfma_f32_32x32x16_bf16 v[64:79], v[222:225], v[192:195], v[64:79]
	v_mfma_f32_32x32x16_bf16 v[112:127], v[176:179], v[164:167], v[112:127]
	v_mfma_f32_32x32x16_bf16 v[96:111], v[184:187], v[164:167], v[96:111]
	v_mfma_f32_32x32x16_bf16 v[112:127], v[180:183], v[192:195], v[112:127]
	ds_read_b128 v[164:167], v204 offset:6144
	ds_read_b128 v[176:179], v204 offset:7168
	ds_read_b128 v[180:183], v204 offset:14336
	ds_read_b128 v[184:187], v204 offset:15360
	ds_read_b128 v[196:199], v204 offset:22528
	ds_read_b128 v[200:203], v204 offset:23552
	ds_read_b128 v[222:225], v204 offset:30720
	ds_read_b128 v[230:233], v204 offset:31744
	v_mfma_f32_32x32x16_bf16 v[96:111], v[188:191], v[192:195], v[96:111]
	v_cvt_pk_bf16_f32 v188, v16, v17
	v_cvt_pk_bf16_f32 v189, v18, v19
	v_cvt_pk_bf16_f32 v190, v20, v21
	v_cvt_pk_bf16_f32 v191, v22, v23
	s_waitcnt lgkmcnt(11)
	s_nop 0
	v_mfma_f32_32x32x16_bf16 v[80:95], v[172:175], v[188:191], v[80:95]
	v_cvt_pk_bf16_f32 v172, v24, v25
	v_cvt_pk_bf16_f32 v173, v26, v27
	v_cvt_pk_bf16_f32 v174, v28, v29
	v_cvt_pk_bf16_f32 v175, v30, v31
	s_waitcnt lgkmcnt(9)
; #define MFMA32(a, b, c) __builtin_amdgcn_mfma_f32_32x32x16_bf16((a), (b), (c), 0, 0, 0)
; #define PACK8(v, base) pack8f((v)[(base) + 0], (v)[(base) + 1], (v)[(base) + 2], (v)[(base) + 3], (v)[(base) + 4], (v)[(base) + 5], (v)[(base) + 6], (v)[(base) + 7])
; #define SBAR() __builtin_amdgcn_sched_barrier(0)
; #define COMP_WQ(f, g) do { _Pragma("unroll") for (int e = 0; e < 2; ++e) { const bf16x8 sb = PACK8(S[(2 * (g) + e) >> 1], ((2 * (g) + e) & 1) * 8); \
;                 vn[0] = MFMA32(f[4 * e], sb, vn[0]); vn[1] = MFMA32(f[4 * e + 1], sb, vn[1]); o[0] = MFMA32(f[4 * e + 2], sb, o[0]); o[1] = MFMA32(f[4 * e + 3], sb, o[1]); } } while (0)
; DI void gdn_scan(const Args& a, int l, int bh, LAS unsigned char* lds, const int tidx, const bool nostore) {
;     ...
;             COMP_WQ(fa, 2); SBAR();
; #pragma unroll
;             for (int e = 0; e < 8; ++e) fa[e] = LDF(49152 + e * 1024);
;             SBAR();
;             COMP_WQ(fb, 3); SBAR();
; #pragma unroll
;             for (int e = 0; e < 8; ++e) fb[e] = LDF(32768 + e * 1024);
;             SBAR();
;             bf16x8 Vb[4];
; #pragma unroll
;             for (int s2 = 0; s2 < 4; ++s2) Vb[s2] = PACK8(vn[s2 >> 1], (s2 & 1) * 8);
; #pragma unroll
;             for (int s2 = 0; s2 < 4; ++s2)
; #pragma unroll
;                 for (int mt = 0; mt < 2; ++mt) o[mt] = MFMA32(fa[mt * 4 + s2], Vb[s2], o[mt]);
;             SBAR();
; #pragma unroll
;             for (int e = 0; e < 8; ++e) fa[e] = LDF(32768 + 8192 + e * 1024);
;             SBAR();
; #pragma unroll
;             for (int t = 0; t < 4; ++t)
; #pragma unroll
;                 for (int r = 0; r < 16; ++r) S[t][r] *= eg;
; #pragma unroll
;             for (int s2 = 0; s2 < 4; ++s2)
; #pragma unroll
;                 for (int t = 0; t < 2; ++t) S[t] = MFMA32(fb[t * 4 + s2], Vb[s2], S[t]);
	v_mfma_f32_32x32x16_bf16 v[64:79], v[234:237], v[188:191], v[64:79]
	v_mfma_f32_32x32x16_bf16 v[80:95], v[226:229], v[172:175], v[80:95]
	s_waitcnt lgkmcnt(8)
	v_mfma_f32_32x32x16_bf16 v[64:79], v[248:251], v[172:175], v[64:79]
	v_mfma_f32_32x32x16_bf16 v[112:127], v[152:155], v[188:191], v[112:127]
	v_mfma_f32_32x32x16_bf16 v[96:111], v[160:163], v[188:191], v[96:111]
	v_mfma_f32_32x32x16_bf16 v[112:127], v[156:159], v[172:175], v[112:127]
	ds_read_b128 v[152:155], v204 offset:49152
	ds_read_b128 v[156:159], v204 offset:50176
	ds_read_b128 v[160:163], v204 offset:51200
	ds_read_b128 v[188:191], v204 offset:52224
	ds_read_b128 v[192:195], v204 offset:53248
	ds_read_b128 v[226:229], v204 offset:54272
	ds_read_b128 v[234:237], v204 offset:55296
	ds_read_b128 v[248:251], v204 offset:56320
	v_mfma_f32_32x32x16_bf16 v[96:111], v[168:171], v[172:175], v[96:111]
	v_cvt_pk_bf16_f32 v168, v0, v1
	v_cvt_pk_bf16_f32 v169, v2, v3
	v_cvt_pk_bf16_f32 v170, v4, v5
	v_cvt_pk_bf16_f32 v171, v6, v7
	v_cvt_pk_bf16_f32 v172, v8, v9
	v_cvt_pk_bf16_f32 v173, v10, v11
	s_waitcnt lgkmcnt(13)
	v_mfma_f32_32x32x16_bf16 v[96:111], v[180:183], v[168:171], v[96:111]
	v_cvt_pk_bf16_f32 v174, v12, v13
	v_cvt_pk_bf16_f32 v175, v14, v15
	s_waitcnt lgkmcnt(11)
	v_mfma_f32_32x32x16_bf16 v[80:95], v[196:199], v[168:171], v[80:95]
	s_waitcnt lgkmcnt(9)
	v_mfma_f32_32x32x16_bf16 v[64:79], v[222:225], v[168:171], v[64:79]
	v_mfma_f32_32x32x16_bf16 v[96:111], v[184:187], v[172:175], v[96:111]
	v_mfma_f32_32x32x16_bf16 v[80:95], v[200:203], v[172:175], v[80:95]
	s_waitcnt lgkmcnt(8)
	v_mfma_f32_32x32x16_bf16 v[64:79], v[230:233], v[172:175], v[64:79]
	v_mfma_f32_32x32x16_bf16 v[112:127], v[164:167], v[168:171], v[112:127]
	ds_read_b128 v[164:167], v204 offset:32768
	ds_read_b128 v[168:171], v204 offset:33792
	ds_read_b128 v[180:183], v204 offset:34816
	ds_read_b128 v[184:187], v204 offset:35840
	ds_read_b128 v[196:199], v204 offset:36864
	ds_read_b128 v[200:203], v204 offset:37888
	ds_read_b128 v[222:225], v204 offset:38912
	ds_read_b128 v[230:233], v204 offset:39936
	v_mfma_f32_32x32x16_bf16 v[112:127], v[176:179], v[172:175], v[112:127]
	s_nop 11
	v_cvt_pk_bf16_f32 v112, v112, v113
	v_cvt_pk_bf16_f32 v113, v114, v115
	v_cvt_pk_bf16_f32 v114, v116, v117
	v_cvt_pk_bf16_f32 v115, v118, v119
	v_cvt_pk_bf16_f32 v116, v120, v121
	v_cvt_pk_bf16_f32 v117, v122, v123
	s_waitcnt lgkmcnt(14)
	v_mfma_f32_32x32x16_bf16 v[80:95], v[152:155], v[112:115], v[80:95]
	v_cvt_pk_bf16_f32 v118, v124, v125
	v_cvt_pk_bf16_f32 v119, v126, v127
	v_cvt_pk_bf16_f32 v96, v96, v97
	v_cvt_pk_bf16_f32 v97, v98, v99
	v_cvt_pk_bf16_f32 v98, v100, v101
	v_cvt_pk_bf16_f32 v99, v102, v103
	v_cvt_pk_bf16_f32 v100, v104, v105
	s_waitcnt lgkmcnt(11)
	v_mfma_f32_32x32x16_bf16 v[64:79], v[192:195], v[112:115], v[64:79]
	v_cvt_pk_bf16_f32 v101, v106, v107
	v_cvt_pk_bf16_f32 v102, v108, v109
	v_cvt_pk_bf16_f32 v103, v110, v111
	v_mfma_f32_32x32x16_bf16 v[80:95], v[156:159], v[116:119], v[80:95]
	s_waitcnt lgkmcnt(10)
	v_mfma_f32_32x32x16_bf16 v[64:79], v[226:229], v[116:119], v[64:79]
	v_mfma_f32_32x32x16_bf16 v[80:95], v[160:163], v[96:99], v[80:95]
	s_waitcnt lgkmcnt(9)
	v_mfma_f32_32x32x16_bf16 v[64:79], v[234:237], v[96:99], v[64:79]
	v_mfma_f32_32x32x16_bf16 v[80:95], v[188:191], v[100:103], v[80:95]
	s_waitcnt lgkmcnt(8)
	v_mfma_f32_32x32x16_bf16 v[64:79], v[248:251], v[100:103], v[64:79]
	ds_read_b128 v[104:107], v204 offset:40960
	ds_read_b128 v[108:111], v204 offset:41984
	ds_read_b128 v[120:123], v204 offset:43008
	ds_read_b128 v[124:127], v204 offset:44032
	ds_read_b128 v[152:155], v204 offset:45056
	ds_read_b128 v[156:159], v204 offset:46080
	ds_read_b128 v[160:163], v204 offset:47104
	ds_read_b128 v[172:175], v204 offset:48128
	s_nop 0
	v_pk_mul_f32 v[62:63], v[62:63], v[148:149] op_sel_hi:[1,0]
	v_pk_mul_f32 v[60:61], v[60:61], v[148:149] op_sel_hi:[1,0]
	v_pk_mul_f32 v[58:59], v[58:59], v[148:149] op_sel_hi:[1,0]
	v_pk_mul_f32 v[56:57], v[56:57], v[148:149] op_sel_hi:[1,0]
	v_pk_mul_f32 v[54:55], v[54:55], v[148:149] op_sel_hi:[1,0]
	v_pk_mul_f32 v[52:53], v[52:53], v[148:149] op_sel_hi:[1,0]
	v_pk_mul_f32 v[50:51], v[50:51], v[148:149] op_sel_hi:[1,0]
	v_pk_mul_f32 v[48:49], v[48:49], v[148:149] op_sel_hi:[1,0]
	v_pk_mul_f32 v[46:47], v[46:47], v[148:149] op_sel_hi:[1,0]
	v_pk_mul_f32 v[44:45], v[44:45], v[148:149] op_sel_hi:[1,0]
	v_pk_mul_f32 v[42:43], v[42:43], v[148:149] op_sel_hi:[1,0]
	v_pk_mul_f32 v[40:41], v[40:41], v[148:149] op_sel_hi:[1,0]
	v_pk_mul_f32 v[38:39], v[38:39], v[148:149] op_sel_hi:[1,0]
	v_pk_mul_f32 v[36:37], v[36:37], v[148:149] op_sel_hi:[1,0]
	v_pk_mul_f32 v[34:35], v[34:35], v[148:149] op_sel_hi:[1,0]
	v_pk_mul_f32 v[32:33], v[32:33], v[148:149] op_sel_hi:[1,0]
	s_waitcnt lgkmcnt(14)
	v_mfma_f32_32x32x16_bf16 v[48:63], v[164:167], v[112:115], v[48:63]
	v_mul_f32_e64 v30, v30, v148
	v_mul_f32_e64 v31, v31, v148
	v_mul_f32_e64 v28, v28, v148
	v_mul_f32_e64 v29, v29, v148
	v_mul_f32_e64 v26, v26, v148
	v_mul_f32_e64 v27, v27, v148
	v_pk_mul_f32 v[24:25], v[24:25], v[148:149] op_sel_hi:[1,0]
	v_pk_mul_f32 v[22:23], v[22:23], v[148:149] op_sel_hi:[1,0]
	v_pk_mul_f32 v[20:21], v[20:21], v[148:149] op_sel_hi:[1,0]
	v_pk_mul_f32 v[18:19], v[18:19], v[148:149] op_sel_hi:[1,0]
	s_waitcnt lgkmcnt(11)
	v_mfma_f32_32x32x16_bf16 v[32:47], v[196:199], v[112:115], v[32:47]
	v_mul_f32_e64 v16, v16, v148
	v_mul_f32_e64 v17, v17, v148
	v_mul_f32_e64 v14, v14, v148
	v_mul_f32_e64 v15, v15, v148
	v_mul_f32_e64 v12, v12, v148
	v_mul_f32_e64 v13, v13, v148
	v_pk_mul_f32 v[10:11], v[10:11], v[148:149] op_sel_hi:[1,0]
	v_pk_mul_f32 v[8:9], v[8:9], v[148:149] op_sel_hi:[1,0]
	v_pk_mul_f32 v[6:7], v[6:7], v[148:149] op_sel_hi:[1,0]
	v_pk_mul_f32 v[4:5], v[4:5], v[148:149] op_sel_hi:[1,0]
	v_mfma_f32_32x32x16_bf16 v[48:63], v[168:171], v[116:119], v[48:63]
	v_mul_f32_e64 v2, v2, v148
	v_mul_f32_e64 v3, v3, v148
	v_mul_f32_e64 v0, v0, v148
	v_mul_f32_e64 v1, v1, v148
	s_waitcnt lgkmcnt(10)
; #define LAS __attribute__((address_space(3)))
; DI unsigned pk2(float lo, float hi) { const f32x2_t v = {lo, hi}; return __builtin_bit_cast(unsigned, __builtin_convertvector(v, bf16x2_t)); }
; #define MFMA32(a, b, c) __builtin_amdgcn_mfma_f32_32x32x16_bf16((a), (b), (c), 0, 0, 0)
; #define LDSBAR() do { asm volatile("s_waitcnt lgkmcnt(0)" ::: "memory"); __builtin_amdgcn_s_barrier(); asm volatile("" ::: "memory"); } while (0)
; #define SBAR() __builtin_amdgcn_sched_barrier(0)
; DI void gdn_scan(const Args& a, int l, int bh, LAS unsigned char* lds, const int tidx, const bool nostore) {
;     ...
;             for (int s2 = 0; s2 < 4; ++s2)
; #pragma unroll
;                 for (int t = 0; t < 2; ++t) S[t] = MFMA32(fb[t * 4 + s2], Vb[s2], S[t]);
;             SBAR();
; #pragma unroll
;             for (int s2 = 0; s2 < 4; ++s2)
; #pragma unroll
;                 for (int t = 2; t < 4; ++t) S[t] = MFMA32(fa[(t - 2) * 4 + s2], Vb[s2], S[t]);
;     ...
;             LAS bf16_t* ost = (LAS bf16_t*)(lds + SCAN_OST + (n & 1) * OST_BYTES) + (4 * hf) * OST_PITCH + wave * 32 + (lane & 31);
; #pragma unroll
;             for (int mt = 0; mt < 2; ++mt)
; #pragma unroll
;                 for (int i = 0; i < 4; ++i) { const unsigned w0 = pk2(o[mt][4 * i], o[mt][4 * i + 1]), w1 = pk2(o[mt][4 * i + 2], o[mt][4 * i + 3]);
;                     LAS bf16_t* d = ost + (mt * 32 + 8 * i) * OST_PITCH;
;                     d[0] = (bf16_t)(w0 & 0xffffu); d[OST_PITCH] = (bf16_t)(w0 >> 16); d[2 * OST_PITCH] = (bf16_t)(w1 & 0xffffu); d[3 * OST_PITCH] = (bf16_t)(w1 >> 16); }
;             LDSBAR();
	v_mfma_f32_32x32x16_bf16 v[32:47], v[200:203], v[116:119], v[32:47]
	v_mfma_f32_32x32x16_bf16 v[48:63], v[180:183], v[96:99], v[48:63]
	s_waitcnt lgkmcnt(9)
	v_mfma_f32_32x32x16_bf16 v[32:47], v[222:225], v[96:99], v[32:47]
	v_mfma_f32_32x32x16_bf16 v[48:63], v[184:187], v[100:103], v[48:63]
	s_waitcnt lgkmcnt(8)
	v_mfma_f32_32x32x16_bf16 v[32:47], v[230:233], v[100:103], v[32:47]
	s_waitcnt lgkmcnt(7)
	v_mfma_f32_32x32x16_bf16 v[16:31], v[104:107], v[112:115], v[16:31]
	s_mulk_i32 s5, 0x4400
	v_cvt_pk_bf16_f32 v80, v80, v81
	v_cvt_pk_bf16_f32 v81, v82, v83
	v_cvt_pk_bf16_f32 v64, v64, v65
	v_cvt_pk_bf16_f32 v65, v66, v67
	s_add_i32 s4, s4, 1
	s_add_u32 s0, s0, 4
	s_waitcnt lgkmcnt(3)
	v_mfma_f32_32x32x16_bf16 v[0:15], v[152:155], v[112:115], v[0:15]
	s_addc_u32 s1, s1, 0
	v_lshl_add_u64 v[144:145], v[144:145], 0, s[10:11]
	v_lshl_add_u64 v[146:147], v[146:147], 0, s[10:11]
	s_cmp_eq_u32 s4, 63
	s_nop 0
	s_nop 0
	v_mfma_f32_32x32x16_bf16 v[16:31], v[108:111], v[116:119], v[16:31]
	s_waitcnt lgkmcnt(2)
	v_mfma_f32_32x32x16_bf16 v[0:15], v[156:159], v[116:119], v[0:15]
	v_mfma_f32_32x32x16_bf16 v[16:31], v[120:123], v[96:99], v[16:31]
	s_waitcnt lgkmcnt(1)
	v_mfma_f32_32x32x16_bf16 v[0:15], v[160:163], v[96:99], v[0:15]
	v_add_u32_e32 v96, s5, v149
	ds_write_b16 v96, v80
	ds_write_b16_d16_hi v96, v80 offset:272
	ds_write_b16 v96, v81 offset:544
	ds_write_b16_d16_hi v96, v81 offset:816
	v_cvt_pk_bf16_f32 v80, v84, v85
	v_cvt_pk_bf16_f32 v81, v86, v87
	ds_write_b16 v96, v80 offset:2176
	ds_write_b16_d16_hi v96, v80 offset:2448
	ds_write_b16 v96, v81 offset:2720
	ds_write_b16_d16_hi v96, v81 offset:2992
	v_cvt_pk_bf16_f32 v80, v88, v89
	v_cvt_pk_bf16_f32 v81, v90, v91
	v_mfma_f32_32x32x16_bf16 v[16:31], v[124:127], v[100:103], v[16:31]
	ds_write_b16 v96, v80 offset:4352
	ds_write_b16_d16_hi v96, v80 offset:4624
	ds_write_b16 v96, v81 offset:4896
	ds_write_b16_d16_hi v96, v81 offset:5168
	v_cvt_pk_bf16_f32 v80, v92, v93
	v_cvt_pk_bf16_f32 v81, v94, v95
	ds_write_b16 v96, v80 offset:6528
	ds_write_b16_d16_hi v96, v80 offset:6800
	ds_write_b16 v96, v81 offset:7072
	ds_write_b16_d16_hi v96, v81 offset:7344
	ds_write_b16 v96, v64 offset:8704
	ds_write_b16_d16_hi v96, v64 offset:8976
	ds_write_b16 v96, v65 offset:9248
	ds_write_b16_d16_hi v96, v65 offset:9520
	v_cvt_pk_bf16_f32 v64, v68, v69
	v_cvt_pk_bf16_f32 v65, v70, v71
	s_waitcnt lgkmcnt(14)
	v_mfma_f32_32x32x16_bf16 v[0:15], v[172:175], v[100:103], v[0:15]
	ds_write_b16 v96, v64 offset:10880
	ds_write_b16_d16_hi v96, v64 offset:11152
	ds_write_b16 v96, v65 offset:11424
	ds_write_b16_d16_hi v96, v65 offset:11696
	v_cvt_pk_bf16_f32 v64, v72, v73
	v_cvt_pk_bf16_f32 v65, v74, v75
	ds_write_b16 v96, v64 offset:13056
	ds_write_b16_d16_hi v96, v64 offset:13328
	ds_write_b16 v96, v65 offset:13600
	ds_write_b16_d16_hi v96, v65 offset:13872
	v_cvt_pk_bf16_f32 v64, v76, v77
	v_cvt_pk_bf16_f32 v65, v78, v79
	ds_write_b16 v96, v64 offset:15232
	ds_write_b16_d16_hi v96, v64 offset:15504
	ds_write_b16 v96, v65 offset:15776
	ds_write_b16_d16_hi v96, v65 offset:16048
	s_waitcnt lgkmcnt(0)
	s_barrier
	s_cbranch_scc0 .LBB0_380
	s_waitcnt vmcnt(5)
	v_add_u32_e32 v96, 0x10000, v150
	v_lshlrev_b32_e32 v80, 16, v132
	v_and_b32_e32 v81, 0xffff0000, v132
	v_lshlrev_b32_e32 v82, 16, v133
	v_and_b32_e32 v83, 0xffff0000, v133
	v_lshlrev_b32_e32 v84, 16, v134
	v_and_b32_e32 v85, 0xffff0000, v134
	v_lshlrev_b32_e32 v86, 16, v135
	v_and_b32_e32 v87, 0xffff0000, v135
	v_lshlrev_b32_e32 v88, 16, v128
	v_and_b32_e32 v89, 0xffff0000, v128
	v_lshlrev_b32_e32 v90, 16, v129
	v_and_b32_e32 v91, 0xffff0000, v129
	v_lshlrev_b32_e32 v92, 16, v130
	v_and_b32_e32 v93, 0xffff0000, v130
	v_lshlrev_b32_e32 v94, 16, v131
	v_and_b32_e32 v95, 0xffff0000, v131
	ds_read_b128 v[128:131], v150 offset:57344
	ds_read_b128 v[132:135], v96
	v_add_u32_e32 v96, 0x12000, v150
	v_add_u32_e32 v100, 0x14000, v150
	v_add_u32_e32 v104, 0x10400, v150
	v_and_b32_e32 v79, 0xffff0000, v139
	v_lshlrev_b32_e32 v64, 16, v140
	v_and_b32_e32 v65, 0xffff0000, v140
	v_lshlrev_b32_e32 v66, 16, v141
	v_and_b32_e32 v67, 0xffff0000, v141
	v_lshlrev_b32_e32 v68, 16, v142
	v_and_b32_e32 v69, 0xffff0000, v142
	v_lshlrev_b32_e32 v70, 16, v143
	v_and_b32_e32 v71, 0xffff0000, v143
	v_lshlrev_b32_e32 v72, 16, v136
	v_and_b32_e32 v73, 0xffff0000, v136
	v_lshlrev_b32_e32 v74, 16, v137
	v_and_b32_e32 v75, 0xffff0000, v137
	v_lshlrev_b32_e32 v76, 16, v138
	v_and_b32_e32 v77, 0xffff0000, v138
	v_lshlrev_b32_e32 v78, 16, v139
	ds_read_b128 v[96:99], v96
	ds_read_b128 v[100:103], v100
	ds_read_b128 v[136:139], v150 offset:58368
	ds_read_b128 v[140:143], v104
	v_add_u32_e32 v104, 0x12400, v150
	ds_read_b128 v[144:147], v104
	v_add_u32_e32 v104, 0x14400, v150
	ds_read_b128 v[152:155], v104
	v_add_u32_e32 v104, 0x10800, v150
	v_add_u32_e32 v105, 0x12800, v150
	ds_read_b128 v[156:159], v104
	ds_read_b128 v[160:163], v105
	v_add_u32_e32 v104, 0x14800, v150
	ds_read_b128 v[164:167], v150 offset:59392
	ds_read_b128 v[168:171], v150 offset:60416
	v_add_u32_e32 v105, 0x10c00, v150
	ds_read_b128 v[172:175], v104
	ds_read_b128 v[176:179], v105
	v_add_u32_e32 v104, 0x12c00, v150
	v_add_u32_e32 v105, 0x14c00, v150
	ds_read_b128 v[180:183], v104
	ds_read_b128 v[184:187], v105
	v_cvt_pk_bf16_f32 v48, v48, v49
	v_cvt_pk_bf16_f32 v49, v50, v51
	v_cvt_pk_bf16_f32 v50, v52, v53
	v_cvt_pk_bf16_f32 v51, v54, v55
	v_cvt_pk_bf16_f32 v52, v56, v57
	v_cvt_pk_bf16_f32 v53, v58, v59
	s_waitcnt lgkmcnt(13)
	v_mfma_f32_32x32x16_bf16 v[112:127], v[96:99], v[48:51], 0
	v_cvt_pk_bf16_f32 v54, v60, v61
	v_cvt_pk_bf16_f32 v55, v62, v63
	s_waitcnt lgkmcnt(12)
	v_mfma_f32_32x32x16_bf16 v[96:111], v[100:103], v[48:51], 0
	s_waitcnt lgkmcnt(9)
; #define LAS __attribute__((address_space(3)))
; #define MFMA32(a, b, c) __builtin_amdgcn_mfma_f32_32x32x16_bf16((a), (b), (c), 0, 0, 0)
; #define PACK8(v, base) pack8f((v)[(base) + 0], (v)[(base) + 1], (v)[(base) + 2], (v)[(base) + 3], (v)[(base) + 4], (v)[(base) + 5], (v)[(base) + 6], (v)[(base) + 7])
; #define SBAR() __builtin_amdgcn_sched_barrier(0)
; #define LOAD_WQ(f, g) do { _Pragma("unroll") for (int e = 0; e < 2; ++e) { f[4 * e] = LDF((2 * (g) + e) * 1024); f[4 * e + 1] = LDF((8 + 2 * (g) + e) * 1024); \
;                 f[4 * e + 2] = LDF(16384 + (2 * (g) + e) * 1024); f[4 * e + 3] = LDF(16384 + (8 + 2 * (g) + e) * 1024); } } while (0)
; #define COMP_WQ(f, g) do { _Pragma("unroll") for (int e = 0; e < 2; ++e) { const bf16x8 sb = PACK8(S[(2 * (g) + e) >> 1], ((2 * (g) + e) & 1) * 8); \
;                 vn[0] = MFMA32(f[4 * e], sb, vn[0]); vn[1] = MFMA32(f[4 * e + 1], sb, vn[1]); o[0] = MFMA32(f[4 * e + 2], sb, o[0]); o[1] = MFMA32(f[4 * e + 3], sb, o[1]); } } while (0)
; DI void gdn_scan(const Args& a, int l, int bh, LAS unsigned char* lds, const int tidx, const bool nostore) {
;     ...
;             const LAS unsigned char* buf = lds + (n & 1) * REC_BYTES + lane * 16;
;             bf16x8 fa[8], fb[8];
;     ...
;             LOAD_WQ(fa, 0); SBAR(); LOAD_WQ(fb, 1); SBAR();
;             COMP_WQ(fa, 0); SBAR(); LOAD_WQ(fa, 2); SBAR();
;             COMP_WQ(fb, 1); SBAR(); LOAD_WQ(fb, 3); SBAR();
;             COMP_WQ(fa, 2); SBAR();
; #pragma unroll
;             for (int e = 0; e < 8; ++e) fa[e] = LDF(49152 + e * 1024);
;             SBAR();
;             COMP_WQ(fb, 3); SBAR();
; #pragma unroll
;             for (int e = 0; e < 8; ++e) fb[e] = LDF(32768 + e * 1024);
;             SBAR();
;             bf16x8 Vb[4];
; #pragma unroll
;             for (int s2 = 0; s2 < 4; ++s2) Vb[s2] = PACK8(vn[s2 >> 1], (s2 & 1) * 8);
; #pragma unroll
;             for (int s2 = 0; s2 < 4; ++s2)
; #pragma unroll
;                 for (int mt = 0; mt < 2; ++mt) o[mt] = MFMA32(fa[mt * 4 + s2], Vb[s2], o[mt]);
	v_mfma_f32_32x32x16_bf16 v[112:127], v[144:147], v[52:55], v[112:127]
	s_waitcnt lgkmcnt(8)
	v_mfma_f32_32x32x16_bf16 v[96:111], v[152:155], v[52:55], v[96:111]
	v_mfma_f32_32x32x16_bf16 v[80:95], v[128:131], v[48:51], v[80:95]
	v_add_u32_e32 v56, 0x13000, v150
	v_add_u32_e32 v144, 0x13400, v150
	v_add_u32_e32 v148, 0x15400, v150
	v_mfma_f32_32x32x16_bf16 v[64:79], v[132:135], v[48:51], v[64:79]
	v_add_u32_e32 v48, 0x11000, v150
	v_add_u32_e32 v132, 0x15000, v150
	ds_read_b128 v[48:51], v48
	ds_read_b128 v[56:59], v56
	ds_read_b128 v[60:63], v150 offset:61440
	ds_read_b128 v[128:131], v150 offset:62464
	v_mfma_f32_32x32x16_bf16 v[80:95], v[136:139], v[52:55], v[80:95]
	v_add_u32_e32 v136, 0x11400, v150
	ds_read_b128 v[132:135], v132
	ds_read_b128 v[136:139], v136
	ds_read_b128 v[144:147], v144
	ds_read_b128 v[152:155], v148
	v_mfma_f32_32x32x16_bf16 v[64:79], v[140:143], v[52:55], v[64:79]
	v_cvt_pk_bf16_f32 v32, v32, v33
	v_cvt_pk_bf16_f32 v33, v34, v35
	v_cvt_pk_bf16_f32 v34, v36, v37
	v_cvt_pk_bf16_f32 v35, v38, v39
	v_cvt_pk_bf16_f32 v36, v40, v41
	v_cvt_pk_bf16_f32 v37, v42, v43
	s_waitcnt lgkmcnt(14)
	v_mfma_f32_32x32x16_bf16 v[112:127], v[160:163], v[32:35], v[112:127]
	v_cvt_pk_bf16_f32 v38, v44, v45
	v_cvt_pk_bf16_f32 v39, v46, v47
	s_waitcnt lgkmcnt(11)
	v_mfma_f32_32x32x16_bf16 v[96:111], v[172:175], v[32:35], v[96:111]
	s_waitcnt lgkmcnt(9)
	v_mfma_f32_32x32x16_bf16 v[112:127], v[180:183], v[36:39], v[112:127]
	s_waitcnt lgkmcnt(8)
	v_mfma_f32_32x32x16_bf16 v[96:111], v[184:187], v[36:39], v[96:111]
	v_mfma_f32_32x32x16_bf16 v[80:95], v[164:167], v[32:35], v[80:95]
	v_add_u32_e32 v40, 0x13800, v150
	v_add_u32_e32 v140, 0x15800, v150
	v_add_u32_e32 v148, 0x11c00, v150
	v_add_u32_e32 v151, 0x15c00, v150
	v_mfma_f32_32x32x16_bf16 v[64:79], v[156:159], v[32:35], v[64:79]
	v_add_u32_e32 v32, 0x11800, v150
	ds_read_b128 v[32:35], v32
	ds_read_b128 v[40:43], v40
	ds_read_b128 v[44:47], v150 offset:63488
	ds_read_b128 v[52:55], v150 offset:64512
	ds_read_b128 v[140:143], v140
	ds_read_b128 v[156:159], v148
	v_add_u32_e32 v148, 0x13c00, v150
	ds_read_b128 v[160:163], v148
	ds_read_b128 v[164:167], v151
	v_mfma_f32_32x32x16_bf16 v[80:95], v[168:171], v[36:39], v[80:95]
	v_mfma_f32_32x32x16_bf16 v[64:79], v[176:179], v[36:39], v[64:79]
	v_cvt_pk_bf16_f32 v16, v16, v17
	v_cvt_pk_bf16_f32 v17, v18, v19
	v_cvt_pk_bf16_f32 v18, v20, v21
	v_cvt_pk_bf16_f32 v19, v22, v23
	v_cvt_pk_bf16_f32 v20, v24, v25
	v_cvt_pk_bf16_f32 v21, v26, v27
	s_waitcnt lgkmcnt(14)
	v_mfma_f32_32x32x16_bf16 v[112:127], v[56:59], v[16:19], v[112:127]
	v_cvt_pk_bf16_f32 v22, v28, v29
	v_cvt_pk_bf16_f32 v23, v30, v31
	s_waitcnt lgkmcnt(11)
	v_mfma_f32_32x32x16_bf16 v[96:111], v[132:135], v[16:19], v[96:111]
	s_waitcnt lgkmcnt(9)
	v_mfma_f32_32x32x16_bf16 v[112:127], v[144:147], v[20:23], v[112:127]
	s_waitcnt lgkmcnt(8)
	v_mfma_f32_32x32x16_bf16 v[96:111], v[152:155], v[20:23], v[96:111]
	v_mfma_f32_32x32x16_bf16 v[80:95], v[60:63], v[16:19], v[80:95]
	v_add_u32_e32 v24, 0x1a000, v150
	v_add_u32_e32 v25, 0x1a400, v150
	v_add_u32_e32 v28, 0x1a800, v150
	v_add_u32_e32 v36, 0x1ac00, v150
	v_add_u32_e32 v56, 0x1b400, v150
	v_add_u32_e32 v60, 0x1b800, v150
	v_mfma_f32_32x32x16_bf16 v[64:79], v[48:51], v[16:19], v[64:79]
	v_add_u32_e32 v48, 0x1b000, v150
	ds_read_b128 v[16:19], v24
	ds_read_b128 v[24:27], v25
	ds_read_b128 v[28:31], v28
	ds_read_b128 v[36:39], v36
	ds_read_b128 v[48:51], v48
	ds_read_b128 v[56:59], v56
	v_mfma_f32_32x32x16_bf16 v[80:95], v[128:131], v[20:23], v[80:95]
	v_add_u32_e32 v128, 0x1bc00, v150
	ds_read_b128 v[60:63], v60
	ds_read_b128 v[128:131], v128
	v_mfma_f32_32x32x16_bf16 v[64:79], v[136:139], v[20:23], v[64:79]
	v_cvt_pk_bf16_f32 v0, v0, v1
	v_cvt_pk_bf16_f32 v1, v2, v3
	v_cvt_pk_bf16_f32 v2, v4, v5
	v_cvt_pk_bf16_f32 v3, v6, v7
	v_cvt_pk_bf16_f32 v4, v8, v9
	v_cvt_pk_bf16_f32 v5, v10, v11
	s_waitcnt lgkmcnt(14)
; #define LAS __attribute__((address_space(3)))
; DI unsigned pk2(float lo, float hi) { const f32x2_t v = {lo, hi}; return __builtin_bit_cast(unsigned, __builtin_convertvector(v, bf16x2_t)); }
; #define MFMA32(a, b, c) __builtin_amdgcn_mfma_f32_32x32x16_bf16((a), (b), (c), 0, 0, 0)
; #define PACK8(v, base) pack8f((v)[(base) + 0], (v)[(base) + 1], (v)[(base) + 2], (v)[(base) + 3], (v)[(base) + 4], (v)[(base) + 5], (v)[(base) + 6], (v)[(base) + 7])
; #define LDSBAR() do { asm volatile("s_waitcnt lgkmcnt(0)" ::: "memory"); __builtin_amdgcn_s_barrier(); asm volatile("" ::: "memory"); } while (0)
; #define SBAR() __builtin_amdgcn_sched_barrier(0)
; DI void gdn_scan(const Args& a, int l, int bh, LAS unsigned char* lds, const int tidx, const bool nostore) {
;     ...
;             for (int s2 = 0; s2 < 4; ++s2) Vb[s2] = PACK8(vn[s2 >> 1], (s2 & 1) * 8);
; #pragma unroll
;             for (int s2 = 0; s2 < 4; ++s2)
; #pragma unroll
;                 for (int mt = 0; mt < 2; ++mt) o[mt] = MFMA32(fa[mt * 4 + s2], Vb[s2], o[mt]);
;             SBAR();
; #pragma unroll
;             for (int e = 0; e < 8; ++e) fa[e] = LDF(32768 + 8192 + e * 1024);
;             SBAR();
; #pragma unroll
;             for (int t = 0; t < 4; ++t)
; #pragma unroll
;                 for (int r = 0; r < 16; ++r) S[t][r] *= eg;
; #pragma unroll
;             for (int s2 = 0; s2 < 4; ++s2)
; #pragma unroll
;                 for (int t = 0; t < 2; ++t) S[t] = MFMA32(fb[t * 4 + s2], Vb[s2], S[t]);
;             SBAR();
; #pragma unroll
;             for (int s2 = 0; s2 < 4; ++s2)
; #pragma unroll
;                 for (int t = 2; t < 4; ++t) S[t] = MFMA32(fa[(t - 2) * 4 + s2], Vb[s2], S[t]);
;     ...
;             LAS bf16_t* ost = (LAS bf16_t*)(lds + SCAN_OST + (n & 1) * OST_BYTES) + (4 * hf) * OST_PITCH + wave * 32 + (lane & 31);
; #pragma unroll
;             for (int mt = 0; mt < 2; ++mt)
; #pragma unroll
;                 for (int i = 0; i < 4; ++i) { const unsigned w0 = pk2(o[mt][4 * i], o[mt][4 * i + 1]), w1 = pk2(o[mt][4 * i + 2], o[mt][4 * i + 3]);
;                     LAS bf16_t* d = ost + (mt * 32 + 8 * i) * OST_PITCH;
;                     d[0] = (bf16_t)(w0 & 0xffffu); d[OST_PITCH] = (bf16_t)(w0 >> 16); d[2 * OST_PITCH] = (bf16_t)(w1 & 0xffffu); d[3 * OST_PITCH] = (bf16_t)(w1 >> 16); }
;             LDSBAR();
;         }
;         __builtin_amdgcn_s_setprio(0);
	v_mfma_f32_32x32x16_bf16 v[64:79], v[32:35], v[0:3], v[64:79]
	v_cvt_pk_bf16_f32 v6, v12, v13
	v_cvt_pk_bf16_f32 v7, v14, v15
	v_mfma_f32_32x32x16_bf16 v[112:127], v[40:43], v[0:3], v[112:127]
	s_waitcnt lgkmcnt(11)
	v_mfma_f32_32x32x16_bf16 v[96:111], v[140:143], v[0:3], v[96:111]
	s_waitcnt lgkmcnt(10)
	v_mfma_f32_32x32x16_bf16 v[64:79], v[156:159], v[4:7], v[64:79]
	s_waitcnt lgkmcnt(9)
	v_mfma_f32_32x32x16_bf16 v[112:127], v[160:163], v[4:7], v[112:127]
	s_waitcnt lgkmcnt(8)
	v_mfma_f32_32x32x16_bf16 v[96:111], v[164:167], v[4:7], v[96:111]
	v_mfma_f32_32x32x16_bf16 v[80:95], v[44:47], v[0:3], v[80:95]
	v_mfma_f32_32x32x16_bf16 v[80:95], v[52:55], v[4:7], v[80:95]
	s_nop 11
	v_cvt_pk_bf16_f32 v0, v80, v81
	v_cvt_pk_bf16_f32 v1, v82, v83
	v_cvt_pk_bf16_f32 v2, v84, v85
	v_cvt_pk_bf16_f32 v3, v86, v87
	s_waitcnt lgkmcnt(7)
	s_nop 0
	v_mfma_f32_32x32x16_bf16 v[112:127], v[16:19], v[0:3], v[112:127]
	s_waitcnt lgkmcnt(3)
	v_mfma_f32_32x32x16_bf16 v[96:111], v[48:51], v[0:3], v[96:111]
	v_cvt_pk_bf16_f32 v0, v88, v89
	v_cvt_pk_bf16_f32 v1, v90, v91
	v_cvt_pk_bf16_f32 v2, v92, v93
	v_cvt_pk_bf16_f32 v3, v94, v95
	s_nop 1
	v_mfma_f32_32x32x16_bf16 v[112:127], v[24:27], v[0:3], v[112:127]
	s_waitcnt lgkmcnt(2)
	v_mfma_f32_32x32x16_bf16 v[96:111], v[56:59], v[0:3], v[96:111]
	v_cvt_pk_bf16_f32 v0, v64, v65
	v_cvt_pk_bf16_f32 v1, v66, v67
	v_cvt_pk_bf16_f32 v2, v68, v69
	v_cvt_pk_bf16_f32 v3, v70, v71
	s_nop 1
	v_mfma_f32_32x32x16_bf16 v[112:127], v[28:31], v[0:3], v[112:127]
	s_waitcnt lgkmcnt(1)
	v_mfma_f32_32x32x16_bf16 v[96:111], v[60:63], v[0:3], v[96:111]
	v_cvt_pk_bf16_f32 v0, v72, v73
	v_cvt_pk_bf16_f32 v1, v74, v75
	v_cvt_pk_bf16_f32 v2, v76, v77
	v_cvt_pk_bf16_f32 v3, v78, v79
	s_nop 1
	v_mfma_f32_32x32x16_bf16 v[112:127], v[36:39], v[0:3], v[112:127]
	s_waitcnt lgkmcnt(0)
	v_mfma_f32_32x32x16_bf16 v[96:111], v[128:131], v[0:3], v[96:111]
	s_nop 9
	v_cvt_pk_bf16_f32 v0, v112, v113
	v_cvt_pk_bf16_f32 v1, v114, v115
	ds_write_b16 v149, v0 offset:17408
	ds_write_b16_d16_hi v149, v0 offset:17680
	ds_write_b16 v149, v1 offset:17952
	ds_write_b16_d16_hi v149, v1 offset:18224
	v_cvt_pk_bf16_f32 v0, v116, v117
	v_cvt_pk_bf16_f32 v1, v118, v119
	ds_write_b16 v149, v0 offset:19584
	ds_write_b16_d16_hi v149, v0 offset:19856
	ds_write_b16 v149, v1 offset:20128
	ds_write_b16_d16_hi v149, v1 offset:20400
	v_cvt_pk_bf16_f32 v0, v120, v121
	v_cvt_pk_bf16_f32 v1, v122, v123
	ds_write_b16 v149, v0 offset:21760
	ds_write_b16_d16_hi v149, v0 offset:22032
	ds_write_b16 v149, v1 offset:22304
	ds_write_b16_d16_hi v149, v1 offset:22576
	v_cvt_pk_bf16_f32 v0, v124, v125
	v_cvt_pk_bf16_f32 v1, v126, v127
	ds_write_b16 v149, v0 offset:23936
	ds_write_b16_d16_hi v149, v0 offset:24208
	ds_write_b16 v149, v1 offset:24480
	ds_write_b16_d16_hi v149, v1 offset:24752
	v_cvt_pk_bf16_f32 v0, v96, v97
	v_cvt_pk_bf16_f32 v1, v98, v99
	ds_write_b16 v149, v0 offset:26112
	ds_write_b16_d16_hi v149, v0 offset:26384
	ds_write_b16 v149, v1 offset:26656
	ds_write_b16_d16_hi v149, v1 offset:26928
	v_cvt_pk_bf16_f32 v0, v100, v101
	v_cvt_pk_bf16_f32 v1, v102, v103
	ds_write_b16 v149, v0 offset:28288
	ds_write_b16_d16_hi v149, v0 offset:28560
	ds_write_b16 v149, v1 offset:28832
	ds_write_b16_d16_hi v149, v1 offset:29104
	v_cvt_pk_bf16_f32 v0, v104, v105
	v_cvt_pk_bf16_f32 v1, v106, v107
	ds_write_b16 v149, v0 offset:30464
	ds_write_b16_d16_hi v149, v0 offset:30736
	ds_write_b16 v149, v1 offset:31008
	ds_write_b16_d16_hi v149, v1 offset:31280
	v_cvt_pk_bf16_f32 v0, v108, v109
	v_cvt_pk_bf16_f32 v1, v110, v111
	ds_write_b16 v149, v0 offset:32640
	ds_write_b16_d16_hi v149, v0 offset:32912
	ds_write_b16 v149, v1 offset:33184
	ds_write_b16_d16_hi v149, v1 offset:33456
	s_waitcnt lgkmcnt(0)
	s_barrier
	s_setprio 0
	v_mov_b64_e32 v[250:251], v[206:207]
	s_waitcnt vmcnt(0)
	v_mov_b64_e32 v[210:211], 0x800
	v_mov_b64_e32 v[212:213], 0x7ff
	v_mov_b32_e32 v214, 0x3f317218
	v_mov_b64_e32 v[216:217], 0x700
	v_mov_b64_e32 v[218:219], 0x6ff
	v_mov_b32_e32 v240, 0x358637bd
	v_mov_b32_e32 v241, 1
	v_mov_b32_e32 v242, 0x41b17218
	v_mov_b32_e32 v243, 0x3600000
